# generic GEMM phase (out-proj/mlp1/mlp2) rewritten by hand: continuous cross-tile software pipeline, mid-K-tile barrier, SGPR-addressed LDS-DMA, MFMA operands swapped for row-per-lane accumulators, LDS
# speedup vs baseline: 1.0793x; 1.0793x over previous
; DI f32x16 zero16() { f32x16 z; for (int i = 0; i < 16; ++i) z[i] = 0.f; return z; }
; DI int opqv(int x) { asm volatile("" : "+v"(x)); return x; }
; #define RAWBAR() { asm volatile("s_waitcnt vmcnt(0) lgkmcnt(0)" ::: "memory"); __builtin_amdgcn_s_barrier(); }
;   const int tid = opqv(threadIdx.x), lane = tid & 63, w = tid >> 6, wm = w >> 2, wn = w & 3, l32 = lane & 31, hf = lane >> 5;
;   f32x16 acc[2][2][2];
; #pragma unroll
;   for (int h = 0; h < 2; ++h)
; #pragma unroll
;     for (int i = 0; i < 2; ++i)
; #pragma unroll
;       for (int j = 0; j < 2; ++j) acc[h][i][j] = zero16();
;   const int nk = nk1 + nk2;
;   const int drow = lane >> 3, dslot = lane & 7, x7 = (l32 >> 1) & 7;
;     ...
;   if (V != 1) GLDS(0, 0);
;   RAWBAR();
;   const int tid = opqv(threadIdx.x), lane = tid & 63, w = tid >> 6, wm = w >> 2, wn = w & 3, l32 = lane & 31, hf = lane >> 5;
;   const int nN = N / 256;
;   for (int lt = blockIdx.x >> 3; lt < 16 * nN; lt += gridDim.x >> 3) {
;     int mt, nt; tile_map(lt, 16, nN, 8, 4, mt, nt);
;     const int m0 = mt * 256, n0 = nt * 256;
;     gemm_tile<V>(A + (size_t)m0 * lda, lda, K / 64, nullptr, 0, 0, Wt + (size_t)n0 * ldb, ldb, smem, [&](f32x16(&acc)[2][2], int moff) {
.LBB0_871:
	s_lshl_b32 s29, s20, 4
	v_readlane_b32 s28, v253, 48
	v_readlane_b32 s30, v253, 50
	s_cmp_ge_u32 s28, s29
	s_cbranch_scc1 .LBB0_882
	s_add_u32 s12, s62, s12
	s_addc_u32 s13, s63, s13
	v_readlane_b32 s31, v251, 0
	s_lshr_b32 s34, s20, 3
	s_lshl_b32 s35, s8, 1
	s_lshl_b32 s36, s10, 1
	s_mul_i32 s37, s36, 5
	s_lshr_b32 s51, s50, 1
	s_sub_u32 s51, s51, 2
	s_and_b32 s31, s31, 7
	s_lshl_b32 s31, s31, 4
	v_lshrrev_b32_e32 v228, 6, v182
	v_and_b32_e32 v229, 63, v182
	v_readfirstlane_b32 s15, v228
	v_and_b32_e32 v230, 31, v229
	v_lshrrev_b32_e32 v231, 5, v229
	v_lshrrev_b32_e32 v232, 3, v229
	v_and_b32_e32 v233, 7, v229
	s_lshl_b32 s14, s15, 12
	s_add_u32 s14, s14, 32
	v_lshrrev_b32_e32 v234, 1, v232
	v_xor_b32_e32 v234, v233, v234
	v_lshlrev_b32_e32 v234, 4, v234
	s_lshl_b32 s53, s15, 2
	s_add_u32 s53, s53, 0
	s_lshl_b32 s53, s53, 3
	v_add_u32_e32 v235, s53, v232
	v_mad_u32_u24 v220, v235, s35, v234
	v_lshrrev_b32_e32 v234, 1, v232
	v_add_u32_e32 v234, 4, v234
	v_xor_b32_e32 v234, v233, v234
	v_lshlrev_b32_e32 v234, 4, v234
	s_lshl_b32 s53, s15, 2
	s_add_u32 s53, s53, 1
	s_lshl_b32 s53, s53, 3
	v_add_u32_e32 v235, s53, v232
	v_mad_u32_u24 v221, v235, s35, v234
	v_lshrrev_b32_e32 v234, 1, v232
	v_xor_b32_e32 v234, v233, v234
	v_lshlrev_b32_e32 v234, 4, v234
	s_lshl_b32 s53, s15, 2
	s_add_u32 s53, s53, 2
	s_lshl_b32 s53, s53, 3
	v_add_u32_e32 v235, s53, v232
	v_mad_u32_u24 v222, v235, s35, v234
	v_lshrrev_b32_e32 v234, 1, v232
	v_add_u32_e32 v234, 4, v234
	v_xor_b32_e32 v234, v233, v234
	v_lshlrev_b32_e32 v234, 4, v234
	s_lshl_b32 s53, s15, 2
	s_add_u32 s53, s53, 3
	s_lshl_b32 s53, s53, 3
	v_add_u32_e32 v235, s53, v232
	v_mad_u32_u24 v223, v235, s35, v234
	v_lshrrev_b32_e32 v236, 1, v230
	v_and_b32_e32 v236, 7, v236
	s_lshr_b32 s53, s15, 2
	s_and_b32 s54, s15, 3
	s_lshl_b32 s55, s53, 14
	s_add_u32 s55, s55, 32
	s_lshl_b32 s56, s54, 13
	s_add_u32 s56, s56, 0x8020
	v_lshlrev_b32_e32 v237, 7, v230
	v_add_u32_e32 v238, s56, v237
	v_add_u32_e32 v237, s55, v237
	v_add_u32_e32 v239, 0, v231
	v_xor_b32_e32 v239, v239, v236
	v_lshlrev_b32_e32 v239, 4, v239
	v_add_u32_e32 v204, v237, v239
	v_add_u32_e32 v212, v238, v239
	v_add_u32_e32 v208, 0x10000, v204
	v_add_u32_e32 v216, 0x10000, v212
	v_add_u32_e32 v239, 2, v231
	v_xor_b32_e32 v239, v239, v236
	v_lshlrev_b32_e32 v239, 4, v239
	v_add_u32_e32 v205, v237, v239
	v_add_u32_e32 v213, v238, v239
	v_add_u32_e32 v209, 0x10000, v205
	v_add_u32_e32 v217, 0x10000, v213
	v_add_u32_e32 v239, 4, v231
	v_xor_b32_e32 v239, v239, v236
	v_lshlrev_b32_e32 v239, 4, v239
	v_add_u32_e32 v206, v237, v239
	v_add_u32_e32 v214, v238, v239
	v_add_u32_e32 v210, 0x10000, v206
	v_add_u32_e32 v218, 0x10000, v214
	v_add_u32_e32 v239, 6, v231
	v_xor_b32_e32 v239, v239, v236
	v_lshlrev_b32_e32 v239, 4, v239
	v_add_u32_e32 v207, v237, v239
	v_add_u32_e32 v215, v238, v239
	v_add_u32_e32 v211, 0x10000, v207
	v_add_u32_e32 v219, 0x10000, v215
	s_add_u32 s40, s14, 0x10000
	v_lshlrev_b32_e32 v234, 7, v230
	v_lshlrev_b32_e32 v235, 3, v231
	v_add3_u32 v234, v234, v235, s40
	v_and_b32_e32 v235, 7, v230
	v_mov_b32_e32 v178, v235
	v_xor_b32_e32 v179, 1, v235
	v_xor_b32_e32 v180, 2, v235
	v_xor_b32_e32 v181, 3, v235
	v_xor_b32_e32 v188, 4, v235
	v_xor_b32_e32 v189, 5, v235
	v_xor_b32_e32 v190, 6, v235
	v_xor_b32_e32 v191, 7, v235
	v_lshl_add_u32 v178, v178, 4, v234
	v_lshl_add_u32 v179, v179, 4, v234
	v_lshl_add_u32 v180, v180, 4, v234
	v_lshl_add_u32 v181, v181, 4, v234
	v_lshl_add_u32 v188, v188, 4, v234
	v_lshl_add_u32 v189, v189, 4, v234
	v_lshl_add_u32 v190, v190, 4, v234
	v_lshl_add_u32 v191, v191, 4, v234
	v_xor_b32_e32 v194, v232, v233
	v_lshlrev_b32_e32 v194, 4, v194
	v_lshl_add_u32 v194, v232, 7, v194
	v_add_u32_e32 v194, s40, v194
	v_lshlrev_b32_e32 v195, 4, v233
	v_mad_u32_u24 v195, v232, s36, v195
	s_lshl_b32 s40, s36, 3
	s_lshl_b32 s58, s53, 7
	s_lshl_b32 s59, s54, 7
	s_mov_b32 s27, s28
	s_mov_b32 s26, 0
	s_lshr_b32 s53, s27, 5
	s_and_b32 s54, s27, 31
	s_lshr_b32 s55, s53, s34
	s_lshl_b32 s56, s55, s34
	s_sub_u32 s56, s53, s56
	s_lshl_b32 s55, s55, 3
	s_add_u32 s55, s55, s31
	s_lshr_b32 s57, s54, 2
	s_add_u32 s55, s55, s57
	s_lshl_b32 s56, s56, 2
	s_and_b32 s57, s54, 3
	s_add_u32 s56, s56, s57
	s_lshl_b32 s57, s55, 8
	s_mul_i32 s57, s57, s35
	s_add_u32 s22, s0, s57
	s_addc_u32 s23, s1, 0
	s_lshl_b32 s57, s56, 8
	s_mul_i32 s57, s57, s35
	s_add_u32 s24, s6, s57
	s_addc_u32 s25, s7, 0
	s_add_u32 m0, s14, 0x0
	s_nop 0
	global_load_lds_dwordx4 v220, s[22:23]
	s_add_u32 m0, s14, 0x8000
	s_nop 0
	global_load_lds_dwordx4 v220, s[24:25]
	s_add_u32 m0, s14, 0x400
	s_nop 0
	global_load_lds_dwordx4 v221, s[22:23]
	s_add_u32 m0, s14, 0x8400
	s_nop 0
	global_load_lds_dwordx4 v221, s[24:25]
	s_add_u32 m0, s14, 0x800
	s_nop 0
	global_load_lds_dwordx4 v222, s[22:23]
	s_add_u32 m0, s14, 0x8800
	s_nop 0
	global_load_lds_dwordx4 v222, s[24:25]
	s_add_u32 m0, s14, 0xc00
	s_nop 0
	global_load_lds_dwordx4 v223, s[22:23]
	s_add_u32 m0, s14, 0x8c00
	s_nop 0
	global_load_lds_dwordx4 v223, s[24:25]
	s_add_u32 s22, s22, 0x80
	s_addc_u32 s23, s23, 0
	s_add_u32 s24, s24, 0x80
	s_addc_u32 s25, s25, 0
	s_add_u32 s26, s26, 1
	s_cmp_eq_u32 s26, s50
	s_cbranch_scc0 .Lgm_cadv_done1
	s_mov_b32 s26, 0
	s_add_u32 s27, s27, s30
	s_cmp_lt_u32 s27, s29
	s_cbranch_scc1 .Lgm_cadv_new1
	s_lshl_b32 s53, s50, 7
	s_sub_u32 s22, s22, s53
	s_subb_u32 s23, s23, 0
	s_sub_u32 s24, s24, s53
	s_subb_u32 s25, s25, 0
	s_branch .Lgm_cadv_done1
.Lgm_cadv_new1:
	s_lshr_b32 s53, s27, 5
	s_and_b32 s54, s27, 31
	s_lshr_b32 s55, s53, s34
	s_lshl_b32 s56, s55, s34
	s_sub_u32 s56, s53, s56
	s_lshl_b32 s55, s55, 3
	s_add_u32 s55, s55, s31
	s_lshr_b32 s57, s54, 2
	s_add_u32 s55, s55, s57
	s_lshl_b32 s56, s56, 2
	s_and_b32 s57, s54, 3
	s_add_u32 s56, s56, s57
	s_lshl_b32 s57, s55, 8
	s_mul_i32 s57, s57, s35
	s_add_u32 s22, s0, s57
	s_addc_u32 s23, s1, 0
	s_lshl_b32 s57, s56, 8
	s_mul_i32 s57, s57, s35
	s_add_u32 s24, s6, s57
	s_addc_u32 s25, s7, 0
.Lgm_cadv_done1:
	s_add_u32 m0, s14, 0x10000
	s_nop 0
	global_load_lds_dwordx4 v220, s[22:23]
	s_add_u32 m0, s14, 0x18000
	s_nop 0
	global_load_lds_dwordx4 v220, s[24:25]
	s_add_u32 m0, s14, 0x10400
	s_nop 0
	global_load_lds_dwordx4 v221, s[22:23]
	s_add_u32 m0, s14, 0x18400
	s_nop 0
	global_load_lds_dwordx4 v221, s[24:25]
	s_add_u32 m0, s14, 0x10800
	s_nop 0
	global_load_lds_dwordx4 v222, s[22:23]
	s_add_u32 m0, s14, 0x18800
	s_nop 0
	global_load_lds_dwordx4 v222, s[24:25]
	s_add_u32 m0, s14, 0x10c00
	s_nop 0
	global_load_lds_dwordx4 v223, s[22:23]
	s_add_u32 m0, s14, 0x18c00
	s_nop 0
	global_load_lds_dwordx4 v223, s[24:25]
	s_add_u32 s22, s22, 0x80
	s_addc_u32 s23, s23, 0
	s_add_u32 s24, s24, 0x80
	s_addc_u32 s25, s25, 0
	s_add_u32 s26, s26, 1
	s_cmp_eq_u32 s26, s50
	s_cbranch_scc0 .Lgm_cadv_done2
	s_mov_b32 s26, 0
	s_add_u32 s27, s27, s30
	s_cmp_lt_u32 s27, s29
	s_cbranch_scc1 .Lgm_cadv_new2
	s_lshl_b32 s53, s50, 7
	s_sub_u32 s22, s22, s53
	s_subb_u32 s23, s23, 0
	s_sub_u32 s24, s24, s53
	s_subb_u32 s25, s25, 0
	s_branch .Lgm_cadv_done2

; #define RAWBAR() { asm volatile("s_waitcnt vmcnt(0) lgkmcnt(0)" ::: "memory"); __builtin_amdgcn_s_barrier(); }
;     ...
;   if (V != 1) GLDS(0, 0);
;   RAWBAR();
;   for (int kt = 0; kt < nk; kt += 2) {
;     if (V != 1) GLDS(kt + 1, 1);
;     if (V != 2) COMPUTE(0);
;     RAWBAR();
.Lgm_cadv_done2:
	s_waitcnt vmcnt(8)
	s_barrier
	ds_read_b128 v[128:131], v204
	ds_read_b128 v[132:135], v204 offset:4096
	ds_read_b128 v[136:139], v204 offset:8192
	ds_read_b128 v[140:143], v204 offset:12288
	ds_read_b128 v[162:165], v212
	ds_read_b128 v[166:169], v212 offset:4096
	ds_read_b128 v[144:147], v205
	ds_read_b128 v[148:151], v205 offset:4096
	ds_read_b128 v[152:155], v205 offset:8192
	ds_read_b128 v[156:159], v205 offset:12288
	ds_read_b128 v[170:173], v213
	ds_read_b128 v[174:177], v213 offset:4096
.Lgm_tile:
	s_waitcnt lgkmcnt(6)
	v_mfma_f32_32x32x16_bf16 v[0:15], v[162:165], v[128:131], 0
	v_mfma_f32_32x32x16_bf16 v[16:31], v[166:169], v[128:131], 0
	ds_read_b128 v[128:131], v206
	v_mfma_f32_32x32x16_bf16 v[32:47], v[162:165], v[132:135], 0
	v_mfma_f32_32x32x16_bf16 v[48:63], v[166:169], v[132:135], 0
	ds_read_b128 v[132:135], v206 offset:4096
	v_mfma_f32_32x32x16_bf16 v[64:79], v[162:165], v[136:139], 0
	v_mfma_f32_32x32x16_bf16 v[80:95], v[166:169], v[136:139], 0
	ds_read_b128 v[136:139], v206 offset:8192
	v_mfma_f32_32x32x16_bf16 v[96:111], v[162:165], v[140:143], 0
	v_mfma_f32_32x32x16_bf16 v[112:127], v[166:169], v[140:143], 0
	ds_read_b128 v[140:143], v206 offset:12288
	ds_read_b128 v[162:165], v214
	ds_read_b128 v[166:169], v214 offset:4096
	s_waitcnt lgkmcnt(6)
	v_mfma_f32_32x32x16_bf16 v[0:15], v[170:173], v[144:147], v[0:15]
	v_mfma_f32_32x32x16_bf16 v[16:31], v[174:177], v[144:147], v[16:31]
	ds_read_b128 v[144:147], v207
	v_mfma_f32_32x32x16_bf16 v[32:47], v[170:173], v[148:151], v[32:47]
	v_mfma_f32_32x32x16_bf16 v[48:63], v[174:177], v[148:151], v[48:63]
	ds_read_b128 v[148:151], v207 offset:4096
	v_mfma_f32_32x32x16_bf16 v[64:79], v[170:173], v[152:155], v[64:79]
	v_mfma_f32_32x32x16_bf16 v[80:95], v[174:177], v[152:155], v[80:95]
	ds_read_b128 v[152:155], v207 offset:8192
	v_mfma_f32_32x32x16_bf16 v[96:111], v[170:173], v[156:159], v[96:111]
	v_mfma_f32_32x32x16_bf16 v[112:127], v[174:177], v[156:159], v[112:127]
	ds_read_b128 v[156:159], v207 offset:12288
	ds_read_b128 v[170:173], v215
	ds_read_b128 v[174:177], v215 offset:4096
	s_waitcnt vmcnt(0) lgkmcnt(0)
	s_barrier
	s_add_u32 m0, s14, 0x0
	v_mfma_f32_32x32x16_bf16 v[0:15], v[162:165], v[128:131], v[0:15]
	global_load_lds_dwordx4 v220, s[22:23]
	s_add_u32 m0, s14, 0x8000
	v_mfma_f32_32x32x16_bf16 v[16:31], v[166:169], v[128:131], v[16:31]
	global_load_lds_dwordx4 v220, s[24:25]
	ds_read_b128 v[128:131], v208
	s_add_u32 m0, s14, 0x400
	v_mfma_f32_32x32x16_bf16 v[32:47], v[162:165], v[132:135], v[32:47]
	global_load_lds_dwordx4 v221, s[22:23]
	s_add_u32 m0, s14, 0x8400
	v_mfma_f32_32x32x16_bf16 v[48:63], v[166:169], v[132:135], v[48:63]
	global_load_lds_dwordx4 v221, s[24:25]
	ds_read_b128 v[132:135], v208 offset:4096
	s_add_u32 m0, s14, 0x800
	v_mfma_f32_32x32x16_bf16 v[64:79], v[162:165], v[136:139], v[64:79]
	global_load_lds_dwordx4 v222, s[22:23]
	s_add_u32 m0, s14, 0x8800
	v_mfma_f32_32x32x16_bf16 v[80:95], v[166:169], v[136:139], v[80:95]
	global_load_lds_dwordx4 v222, s[24:25]
	ds_read_b128 v[136:139], v208 offset:8192
	s_add_u32 m0, s14, 0xc00
	v_mfma_f32_32x32x16_bf16 v[96:111], v[162:165], v[140:143], v[96:111]
	global_load_lds_dwordx4 v223, s[22:23]
	s_add_u32 m0, s14, 0x8c00
	v_mfma_f32_32x32x16_bf16 v[112:127], v[166:169], v[140:143], v[112:127]
	global_load_lds_dwordx4 v223, s[24:25]
	ds_read_b128 v[140:143], v208 offset:12288
	ds_read_b128 v[162:165], v216
	ds_read_b128 v[166:169], v216 offset:4096
	v_mfma_f32_32x32x16_bf16 v[0:15], v[170:173], v[144:147], v[0:15]
	v_mfma_f32_32x32x16_bf16 v[16:31], v[174:177], v[144:147], v[16:31]
	ds_read_b128 v[144:147], v209
	v_mfma_f32_32x32x16_bf16 v[32:47], v[170:173], v[148:151], v[32:47]
	v_mfma_f32_32x32x16_bf16 v[48:63], v[174:177], v[148:151], v[48:63]
	ds_read_b128 v[148:151], v209 offset:4096
	v_mfma_f32_32x32x16_bf16 v[64:79], v[170:173], v[152:155], v[64:79]
	v_mfma_f32_32x32x16_bf16 v[80:95], v[174:177], v[152:155], v[80:95]
	ds_read_b128 v[152:155], v209 offset:8192
	v_mfma_f32_32x32x16_bf16 v[96:111], v[170:173], v[156:159], v[96:111]
	v_mfma_f32_32x32x16_bf16 v[112:127], v[174:177], v[156:159], v[112:127]
	ds_read_b128 v[156:159], v209 offset:12288
	ds_read_b128 v[170:173], v217
	ds_read_b128 v[174:177], v217 offset:4096
	s_add_u32 s22, s22, 0x80
	s_addc_u32 s23, s23, 0
	s_add_u32 s24, s24, 0x80
	s_addc_u32 s25, s25, 0
	s_add_u32 s26, s26, 1
	s_cmp_eq_u32 s26, s50
	s_cbranch_scc0 .Lgm_cadv_done3
	s_mov_b32 s26, 0
	s_add_u32 s27, s27, s30
	s_cmp_lt_u32 s27, s29
	s_cbranch_scc1 .Lgm_cadv_new3
	s_lshl_b32 s53, s50, 7
	s_sub_u32 s22, s22, s53
	s_subb_u32 s23, s23, 0
	s_sub_u32 s24, s24, s53
	s_subb_u32 s25, s25, 0
	s_branch .Lgm_cadv_done3

; #define RAWBAR() { asm volatile("s_waitcnt vmcnt(0) lgkmcnt(0)" ::: "memory"); __builtin_amdgcn_s_barrier(); }
;     ...
;   if (V != 1) GLDS(0, 0);
;   RAWBAR();
;   for (int kt = 0; kt < nk; kt += 2) {
;     if (V != 1) GLDS(kt + 1, 1);
;     if (V != 2) COMPUTE(0);
;     RAWBAR();
;     if (V != 1) if (kt + 2 < nk) GLDS(kt + 2, 0);
;     if (V != 2) COMPUTE(1);
;     RAWBAR();
.Lgm_cadv_done3:
	s_waitcnt lgkmcnt(6)
	v_mfma_f32_32x32x16_bf16 v[0:15], v[162:165], v[128:131], v[0:15]
	v_mfma_f32_32x32x16_bf16 v[16:31], v[166:169], v[128:131], v[16:31]
	ds_read_b128 v[128:131], v210
	v_mfma_f32_32x32x16_bf16 v[32:47], v[162:165], v[132:135], v[32:47]
	v_mfma_f32_32x32x16_bf16 v[48:63], v[166:169], v[132:135], v[48:63]
	ds_read_b128 v[132:135], v210 offset:4096
	v_mfma_f32_32x32x16_bf16 v[64:79], v[162:165], v[136:139], v[64:79]
	v_mfma_f32_32x32x16_bf16 v[80:95], v[166:169], v[136:139], v[80:95]
	ds_read_b128 v[136:139], v210 offset:8192
	v_mfma_f32_32x32x16_bf16 v[96:111], v[162:165], v[140:143], v[96:111]
	v_mfma_f32_32x32x16_bf16 v[112:127], v[166:169], v[140:143], v[112:127]
	ds_read_b128 v[140:143], v210 offset:12288
	ds_read_b128 v[162:165], v218
	ds_read_b128 v[166:169], v218 offset:4096
	s_waitcnt lgkmcnt(6)
	v_mfma_f32_32x32x16_bf16 v[0:15], v[170:173], v[144:147], v[0:15]
	v_mfma_f32_32x32x16_bf16 v[16:31], v[174:177], v[144:147], v[16:31]
	ds_read_b128 v[144:147], v211
	v_mfma_f32_32x32x16_bf16 v[32:47], v[170:173], v[148:151], v[32:47]
	v_mfma_f32_32x32x16_bf16 v[48:63], v[174:177], v[148:151], v[48:63]
	ds_read_b128 v[148:151], v211 offset:4096
	v_mfma_f32_32x32x16_bf16 v[64:79], v[170:173], v[152:155], v[64:79]
	v_mfma_f32_32x32x16_bf16 v[80:95], v[174:177], v[152:155], v[80:95]
	ds_read_b128 v[152:155], v211 offset:8192
	v_mfma_f32_32x32x16_bf16 v[96:111], v[170:173], v[156:159], v[96:111]
	v_mfma_f32_32x32x16_bf16 v[112:127], v[174:177], v[156:159], v[112:127]
	ds_read_b128 v[156:159], v211 offset:12288
	ds_read_b128 v[170:173], v219
	ds_read_b128 v[174:177], v219 offset:4096
	s_waitcnt vmcnt(0) lgkmcnt(0)
	s_barrier
	s_add_u32 m0, s14, 0x10000
	v_mfma_f32_32x32x16_bf16 v[0:15], v[162:165], v[128:131], v[0:15]
	global_load_lds_dwordx4 v220, s[22:23]
	s_add_u32 m0, s14, 0x18000
	v_mfma_f32_32x32x16_bf16 v[16:31], v[166:169], v[128:131], v[16:31]
	global_load_lds_dwordx4 v220, s[24:25]
	ds_read_b128 v[128:131], v204
	s_add_u32 m0, s14, 0x10400
	v_mfma_f32_32x32x16_bf16 v[32:47], v[162:165], v[132:135], v[32:47]
	global_load_lds_dwordx4 v221, s[22:23]
	s_add_u32 m0, s14, 0x18400
	v_mfma_f32_32x32x16_bf16 v[48:63], v[166:169], v[132:135], v[48:63]
	global_load_lds_dwordx4 v221, s[24:25]
	ds_read_b128 v[132:135], v204 offset:4096
	s_add_u32 m0, s14, 0x10800
	v_mfma_f32_32x32x16_bf16 v[64:79], v[162:165], v[136:139], v[64:79]
	global_load_lds_dwordx4 v222, s[22:23]
	s_add_u32 m0, s14, 0x18800
	v_mfma_f32_32x32x16_bf16 v[80:95], v[166:169], v[136:139], v[80:95]
	global_load_lds_dwordx4 v222, s[24:25]
	ds_read_b128 v[136:139], v204 offset:8192
	s_add_u32 m0, s14, 0x10c00
	v_mfma_f32_32x32x16_bf16 v[96:111], v[162:165], v[140:143], v[96:111]
	global_load_lds_dwordx4 v223, s[22:23]
	s_add_u32 m0, s14, 0x18c00
	v_mfma_f32_32x32x16_bf16 v[112:127], v[166:169], v[140:143], v[112:127]
	global_load_lds_dwordx4 v223, s[24:25]
	ds_read_b128 v[140:143], v204 offset:12288
	ds_read_b128 v[162:165], v212
	ds_read_b128 v[166:169], v212 offset:4096
	v_mfma_f32_32x32x16_bf16 v[0:15], v[170:173], v[144:147], v[0:15]
	v_mfma_f32_32x32x16_bf16 v[16:31], v[174:177], v[144:147], v[16:31]
	ds_read_b128 v[144:147], v205
	v_mfma_f32_32x32x16_bf16 v[32:47], v[170:173], v[148:151], v[32:47]
	v_mfma_f32_32x32x16_bf16 v[48:63], v[174:177], v[148:151], v[48:63]
	ds_read_b128 v[148:151], v205 offset:4096
	v_mfma_f32_32x32x16_bf16 v[64:79], v[170:173], v[152:155], v[64:79]
	v_mfma_f32_32x32x16_bf16 v[80:95], v[174:177], v[152:155], v[80:95]
	ds_read_b128 v[152:155], v205 offset:8192
	v_mfma_f32_32x32x16_bf16 v[96:111], v[170:173], v[156:159], v[96:111]
	v_mfma_f32_32x32x16_bf16 v[112:127], v[174:177], v[156:159], v[112:127]
	ds_read_b128 v[156:159], v205 offset:12288
	ds_read_b128 v[170:173], v213
	ds_read_b128 v[174:177], v213 offset:4096
	s_add_u32 s22, s22, 0x80
	s_addc_u32 s23, s23, 0
	s_add_u32 s24, s24, 0x80
	s_addc_u32 s25, s25, 0
	s_add_u32 s26, s26, 1
	s_cmp_eq_u32 s26, s50
	s_cbranch_scc0 .Lgm_cadv_done4
	s_mov_b32 s26, 0
	s_add_u32 s27, s27, s30
	s_cmp_lt_u32 s27, s29
	s_cbranch_scc1 .Lgm_cadv_new4
	s_lshl_b32 s53, s50, 7
	s_sub_u32 s22, s22, s53
	s_subb_u32 s23, s23, 0
	s_sub_u32 s24, s24, s53
	s_subb_u32 s25, s25, 0
	s_branch .Lgm_cadv_done4

; #define RAWBAR() { asm volatile("s_waitcnt vmcnt(0) lgkmcnt(0)" ::: "memory"); __builtin_amdgcn_s_barrier(); }
;     ...
;   for (int kt = 0; kt < nk; kt += 2) {
;     if (V != 1) GLDS(kt + 1, 1);
;     if (V != 2) COMPUTE(0);
;     RAWBAR();
;     if (V != 1) if (kt + 2 < nk) GLDS(kt + 2, 0);
;     if (V != 2) COMPUTE(1);
;     RAWBAR();
.Lgm_cadv_done4:
	s_mov_b32 s52, s51
	s_cmp_eq_u32 s52, 0
	s_cbranch_scc1 .Lgm_pairs_done
.Lgm_pair:
	s_waitcnt lgkmcnt(6)
	v_mfma_f32_32x32x16_bf16 v[0:15], v[162:165], v[128:131], v[0:15]
	v_mfma_f32_32x32x16_bf16 v[16:31], v[166:169], v[128:131], v[16:31]
	ds_read_b128 v[128:131], v206
	v_mfma_f32_32x32x16_bf16 v[32:47], v[162:165], v[132:135], v[32:47]
	v_mfma_f32_32x32x16_bf16 v[48:63], v[166:169], v[132:135], v[48:63]
	ds_read_b128 v[132:135], v206 offset:4096
	v_mfma_f32_32x32x16_bf16 v[64:79], v[162:165], v[136:139], v[64:79]
	v_mfma_f32_32x32x16_bf16 v[80:95], v[166:169], v[136:139], v[80:95]
	ds_read_b128 v[136:139], v206 offset:8192
	v_mfma_f32_32x32x16_bf16 v[96:111], v[162:165], v[140:143], v[96:111]
	v_mfma_f32_32x32x16_bf16 v[112:127], v[166:169], v[140:143], v[112:127]
	ds_read_b128 v[140:143], v206 offset:12288
	ds_read_b128 v[162:165], v214
	ds_read_b128 v[166:169], v214 offset:4096
	s_waitcnt lgkmcnt(6)
	v_mfma_f32_32x32x16_bf16 v[0:15], v[170:173], v[144:147], v[0:15]
	v_mfma_f32_32x32x16_bf16 v[16:31], v[174:177], v[144:147], v[16:31]
	ds_read_b128 v[144:147], v207
	v_mfma_f32_32x32x16_bf16 v[32:47], v[170:173], v[148:151], v[32:47]
	v_mfma_f32_32x32x16_bf16 v[48:63], v[174:177], v[148:151], v[48:63]
	ds_read_b128 v[148:151], v207 offset:4096
	v_mfma_f32_32x32x16_bf16 v[64:79], v[170:173], v[152:155], v[64:79]
	v_mfma_f32_32x32x16_bf16 v[80:95], v[174:177], v[152:155], v[80:95]
	ds_read_b128 v[152:155], v207 offset:8192
	v_mfma_f32_32x32x16_bf16 v[96:111], v[170:173], v[156:159], v[96:111]
	v_mfma_f32_32x32x16_bf16 v[112:127], v[174:177], v[156:159], v[112:127]
	ds_read_b128 v[156:159], v207 offset:12288
	ds_read_b128 v[170:173], v215
	ds_read_b128 v[174:177], v215 offset:4096
	s_waitcnt vmcnt(0) lgkmcnt(0)
	s_barrier
	s_add_u32 m0, s14, 0x0
	v_mfma_f32_32x32x16_bf16 v[0:15], v[162:165], v[128:131], v[0:15]
	global_load_lds_dwordx4 v220, s[22:23]
	s_add_u32 m0, s14, 0x8000
	v_mfma_f32_32x32x16_bf16 v[16:31], v[166:169], v[128:131], v[16:31]
	global_load_lds_dwordx4 v220, s[24:25]
	ds_read_b128 v[128:131], v208
	s_add_u32 m0, s14, 0x400
	v_mfma_f32_32x32x16_bf16 v[32:47], v[162:165], v[132:135], v[32:47]
	global_load_lds_dwordx4 v221, s[22:23]
	s_add_u32 m0, s14, 0x8400
	v_mfma_f32_32x32x16_bf16 v[48:63], v[166:169], v[132:135], v[48:63]
	global_load_lds_dwordx4 v221, s[24:25]
	ds_read_b128 v[132:135], v208 offset:4096
	s_add_u32 m0, s14, 0x800
	v_mfma_f32_32x32x16_bf16 v[64:79], v[162:165], v[136:139], v[64:79]
	global_load_lds_dwordx4 v222, s[22:23]
	s_add_u32 m0, s14, 0x8800
	v_mfma_f32_32x32x16_bf16 v[80:95], v[166:169], v[136:139], v[80:95]
	global_load_lds_dwordx4 v222, s[24:25]
	ds_read_b128 v[136:139], v208 offset:8192
	s_add_u32 m0, s14, 0xc00
	v_mfma_f32_32x32x16_bf16 v[96:111], v[162:165], v[140:143], v[96:111]
	global_load_lds_dwordx4 v223, s[22:23]
	s_add_u32 m0, s14, 0x8c00
	v_mfma_f32_32x32x16_bf16 v[112:127], v[166:169], v[140:143], v[112:127]
	global_load_lds_dwordx4 v223, s[24:25]
	ds_read_b128 v[140:143], v208 offset:12288
	ds_read_b128 v[162:165], v216
	ds_read_b128 v[166:169], v216 offset:4096
	v_mfma_f32_32x32x16_bf16 v[0:15], v[170:173], v[144:147], v[0:15]
	v_mfma_f32_32x32x16_bf16 v[16:31], v[174:177], v[144:147], v[16:31]
	ds_read_b128 v[144:147], v209
	v_mfma_f32_32x32x16_bf16 v[32:47], v[170:173], v[148:151], v[32:47]
	v_mfma_f32_32x32x16_bf16 v[48:63], v[174:177], v[148:151], v[48:63]
	ds_read_b128 v[148:151], v209 offset:4096
	v_mfma_f32_32x32x16_bf16 v[64:79], v[170:173], v[152:155], v[64:79]
	v_mfma_f32_32x32x16_bf16 v[80:95], v[174:177], v[152:155], v[80:95]
	ds_read_b128 v[152:155], v209 offset:8192
	v_mfma_f32_32x32x16_bf16 v[96:111], v[170:173], v[156:159], v[96:111]
	v_mfma_f32_32x32x16_bf16 v[112:127], v[174:177], v[156:159], v[112:127]
	ds_read_b128 v[156:159], v209 offset:12288
	ds_read_b128 v[170:173], v217
	ds_read_b128 v[174:177], v217 offset:4096
	s_add_u32 s22, s22, 0x80
	s_addc_u32 s23, s23, 0
	s_add_u32 s24, s24, 0x80
	s_addc_u32 s25, s25, 0
	s_add_u32 s26, s26, 1
	s_cmp_eq_u32 s26, s50
	s_cbranch_scc0 .Lgm_cadv_done5
	s_mov_b32 s26, 0
	s_add_u32 s27, s27, s30
	s_cmp_lt_u32 s27, s29
	s_cbranch_scc1 .Lgm_cadv_new5
	s_lshl_b32 s53, s50, 7
	s_sub_u32 s22, s22, s53
	s_subb_u32 s23, s23, 0
	s_sub_u32 s24, s24, s53
	s_subb_u32 s25, s25, 0
	s_branch .Lgm_cadv_done5

; #define RAWBAR() { asm volatile("s_waitcnt vmcnt(0) lgkmcnt(0)" ::: "memory"); __builtin_amdgcn_s_barrier(); }
;     ...
;   for (int kt = 0; kt < nk; kt += 2) {
;     if (V != 1) GLDS(kt + 1, 1);
;     if (V != 2) COMPUTE(0);
;     RAWBAR();
;     if (V != 1) if (kt + 2 < nk) GLDS(kt + 2, 0);
;     if (V != 2) COMPUTE(1);
;     RAWBAR();
;   }
.Lgm_cadv_done6:
	s_sub_u32 s52, s52, 1
	s_cmp_lg_u32 s52, 0
	s_cbranch_scc1 .Lgm_pair

; DI int crow(int r, int hf) { return (r & 3) + 8 * (r >> 2) + 4 * hf; }
; #define RAWBAR() { asm volatile("s_waitcnt vmcnt(0) lgkmcnt(0)" ::: "memory"); __builtin_amdgcn_s_barrier(); }
;     ...
;   for (int kt = 0; kt < nk; kt += 2) {
;     if (V != 1) GLDS(kt + 1, 1);
;     if (V != 2) COMPUTE(0);
;     RAWBAR();
;     if (V != 1) if (kt + 2 < nk) GLDS(kt + 2, 0);
;     if (V != 2) COMPUTE(1);
;     RAWBAR();
;     ...
;     gemm_tile<V>(A + (size_t)m0 * lda, lda, K / 64, nullptr, 0, 0, Wt + (size_t)n0 * ldb, ldb, smem, [&](f32x16(&acc)[2][2], int moff) {
;       const int m0_ = m0 + moff;
;       int l32_ = l32, hf_ = hf; asm volatile("" : "+v"(l32_), "+v"(hf_));
; #pragma unroll
;       for (int i = 0; i < 2; ++i)
; #pragma unroll
;         for (int j = 0; j < 2; ++j)
; #pragma unroll
;           for (int r = 0; r < 16; ++r) {
;             const int row = m0_ + wm * 64 + i * 32 + crow(r, hf_), col = n0 + wn * 64 + j * 32 + l32_;
;             float v = acc[i][j][r];
;             if (mode == 1) { v = fmaxf(v, 0.f); v = v * v; }
;             if (V == 0 || v == 123456.789f) C[(size_t)row * ldc + col] = f2bf(v);
;           }
;     });
.Lgm_cadv_done7:
	s_waitcnt lgkmcnt(6)
	v_mfma_f32_32x32x16_bf16 v[0:15], v[162:165], v[128:131], v[0:15]
	v_mfma_f32_32x32x16_bf16 v[16:31], v[166:169], v[128:131], v[16:31]
	ds_read_b128 v[128:131], v210
	v_mfma_f32_32x32x16_bf16 v[32:47], v[162:165], v[132:135], v[32:47]
	v_mfma_f32_32x32x16_bf16 v[48:63], v[166:169], v[132:135], v[48:63]
	ds_read_b128 v[132:135], v210 offset:4096
	v_mfma_f32_32x32x16_bf16 v[64:79], v[162:165], v[136:139], v[64:79]
	v_mfma_f32_32x32x16_bf16 v[80:95], v[166:169], v[136:139], v[80:95]
	ds_read_b128 v[136:139], v210 offset:8192
	v_mfma_f32_32x32x16_bf16 v[96:111], v[162:165], v[140:143], v[96:111]
	v_mfma_f32_32x32x16_bf16 v[112:127], v[166:169], v[140:143], v[112:127]
	ds_read_b128 v[140:143], v210 offset:12288
	ds_read_b128 v[162:165], v218
	ds_read_b128 v[166:169], v218 offset:4096
	s_waitcnt lgkmcnt(6)
	v_mfma_f32_32x32x16_bf16 v[0:15], v[170:173], v[144:147], v[0:15]
	v_mfma_f32_32x32x16_bf16 v[16:31], v[174:177], v[144:147], v[16:31]
	ds_read_b128 v[144:147], v211
	v_mfma_f32_32x32x16_bf16 v[32:47], v[170:173], v[148:151], v[32:47]
	v_mfma_f32_32x32x16_bf16 v[48:63], v[174:177], v[148:151], v[48:63]
	ds_read_b128 v[148:151], v211 offset:4096
	v_mfma_f32_32x32x16_bf16 v[64:79], v[170:173], v[152:155], v[64:79]
	v_mfma_f32_32x32x16_bf16 v[80:95], v[174:177], v[152:155], v[80:95]
	ds_read_b128 v[152:155], v211 offset:8192
	v_mfma_f32_32x32x16_bf16 v[96:111], v[170:173], v[156:159], v[96:111]
	v_mfma_f32_32x32x16_bf16 v[112:127], v[174:177], v[156:159], v[112:127]
	ds_read_b128 v[156:159], v211 offset:12288
	ds_read_b128 v[170:173], v219
	ds_read_b128 v[174:177], v219 offset:4096
	s_waitcnt vmcnt(0) lgkmcnt(0)
	s_barrier
	s_add_u32 m0, s14, 0x10000
	v_mfma_f32_32x32x16_bf16 v[0:15], v[162:165], v[128:131], v[0:15]
	global_load_lds_dwordx4 v220, s[22:23]
	s_add_u32 m0, s14, 0x10400
	v_mfma_f32_32x32x16_bf16 v[16:31], v[166:169], v[128:131], v[16:31]
	global_load_lds_dwordx4 v221, s[22:23]
	ds_read_b128 v[128:131], v204
	s_add_u32 m0, s14, 0x10800
	v_mfma_f32_32x32x16_bf16 v[32:47], v[162:165], v[132:135], v[32:47]
	global_load_lds_dwordx4 v222, s[22:23]
	s_add_u32 m0, s14, 0x10c00
	v_mfma_f32_32x32x16_bf16 v[48:63], v[166:169], v[132:135], v[48:63]
	global_load_lds_dwordx4 v223, s[22:23]
	ds_read_b128 v[132:135], v204 offset:4096
	v_mfma_f32_32x32x16_bf16 v[64:79], v[162:165], v[136:139], v[64:79]
	v_mfma_f32_32x32x16_bf16 v[80:95], v[166:169], v[136:139], v[80:95]
	ds_read_b128 v[136:139], v204 offset:8192
	v_mfma_f32_32x32x16_bf16 v[96:111], v[162:165], v[140:143], v[96:111]
	v_mfma_f32_32x32x16_bf16 v[112:127], v[166:169], v[140:143], v[112:127]
	ds_read_b128 v[140:143], v204 offset:12288
	ds_read_b128 v[162:165], v212
	ds_read_b128 v[166:169], v212 offset:4096
	v_mfma_f32_32x32x16_bf16 v[0:15], v[170:173], v[144:147], v[0:15]
	v_mfma_f32_32x32x16_bf16 v[16:31], v[174:177], v[144:147], v[16:31]
	ds_read_b128 v[144:147], v205
	v_mfma_f32_32x32x16_bf16 v[32:47], v[170:173], v[148:151], v[32:47]
	v_mfma_f32_32x32x16_bf16 v[48:63], v[174:177], v[148:151], v[48:63]
	ds_read_b128 v[148:151], v205 offset:4096
	v_mfma_f32_32x32x16_bf16 v[64:79], v[170:173], v[152:155], v[64:79]
	v_mfma_f32_32x32x16_bf16 v[80:95], v[174:177], v[152:155], v[80:95]
	ds_read_b128 v[152:155], v205 offset:8192
	v_mfma_f32_32x32x16_bf16 v[96:111], v[170:173], v[156:159], v[96:111]
	v_mfma_f32_32x32x16_bf16 v[112:127], v[174:177], v[156:159], v[112:127]
	ds_read_b128 v[156:159], v205 offset:12288
	ds_read_b128 v[170:173], v213
	ds_read_b128 v[174:177], v213 offset:4096
	s_lshr_b32 s53, s28, 5
	s_and_b32 s54, s28, 31
	s_lshr_b32 s55, s53, s34
	s_lshl_b32 s56, s55, s34
	s_sub_u32 s56, s53, s56
	s_lshl_b32 s55, s55, 3
	s_add_u32 s55, s55, s31
	s_lshr_b32 s57, s54, 2
	s_add_u32 s55, s55, s57
	s_lshl_b32 s56, s56, 2
	s_and_b32 s57, s54, 3
	s_add_u32 s56, s56, s57
	s_lshl_b32 s57, s55, 8
	s_add_u32 s57, s57, s58
	s_mul_i32 s57, s57, s36
	s_add_u32 s38, s12, s57
	s_addc_u32 s39, s13, 0
	s_lshl_b32 s57, s56, 9
	s_add_u32 s57, s57, s59
	s_add_u32 s38, s38, s57
	s_addc_u32 s39, s39, 0
	s_cmp_eq_u64 s[4:5], 0
	s_cbranch_scc1 .Lgm_epi_relu
	v_cvt_pk_bf16_f32 v238, v0, v1
	v_cvt_pk_bf16_f32 v239, v2, v3
	ds_write_b64 v178, v[238:239] offset:32768
	v_cvt_pk_bf16_f32 v240, v4, v5
	v_cvt_pk_bf16_f32 v241, v6, v7
	ds_write_b64 v179, v[240:241] offset:32768
	v_cvt_pk_bf16_f32 v242, v8, v9
	v_cvt_pk_bf16_f32 v243, v10, v11
	ds_write_b64 v180, v[242:243] offset:32768
	v_cvt_pk_bf16_f32 v244, v12, v13
	v_cvt_pk_bf16_f32 v245, v14, v15
	ds_write_b64 v181, v[244:245] offset:32768
	v_cvt_pk_bf16_f32 v238, v16, v17
	v_cvt_pk_bf16_f32 v239, v18, v19
	ds_write_b64 v188, v[238:239] offset:32768
	v_cvt_pk_bf16_f32 v240, v20, v21
	v_cvt_pk_bf16_f32 v241, v22, v23
	ds_write_b64 v189, v[240:241] offset:32768
	v_cvt_pk_bf16_f32 v242, v24, v25
	v_cvt_pk_bf16_f32 v243, v26, v27
	ds_write_b64 v190, v[242:243] offset:32768
	v_cvt_pk_bf16_f32 v244, v28, v29
	v_cvt_pk_bf16_f32 v245, v30, v31
	ds_write_b64 v191, v[244:245] offset:32768
	ds_read_b128 v[0:3], v194 offset:32768
	ds_read_b128 v[4:7], v194 offset:33792
	ds_read_b128 v[8:11], v194 offset:34816
	ds_read_b128 v[12:15], v194 offset:35840
	v_cvt_pk_bf16_f32 v238, v32, v33
	v_cvt_pk_bf16_f32 v239, v34, v35
	ds_write_b64 v178, v[238:239] offset:32768
	v_cvt_pk_bf16_f32 v240, v36, v37
	v_cvt_pk_bf16_f32 v241, v38, v39
	ds_write_b64 v179, v[240:241] offset:32768
	v_cvt_pk_bf16_f32 v242, v40, v41
	v_cvt_pk_bf16_f32 v243, v42, v43
	ds_write_b64 v180, v[242:243] offset:32768
	v_cvt_pk_bf16_f32 v244, v44, v45
	v_cvt_pk_bf16_f32 v245, v46, v47
	ds_write_b64 v181, v[244:245] offset:32768
	v_cvt_pk_bf16_f32 v238, v48, v49
	v_cvt_pk_bf16_f32 v239, v50, v51
	ds_write_b64 v188, v[238:239] offset:32768
	v_cvt_pk_bf16_f32 v240, v52, v53
	v_cvt_pk_bf16_f32 v241, v54, v55
	ds_write_b64 v189, v[240:241] offset:32768
	v_cvt_pk_bf16_f32 v242, v56, v57
	v_cvt_pk_bf16_f32 v243, v58, v59
	ds_write_b64 v190, v[242:243] offset:32768
	v_cvt_pk_bf16_f32 v244, v60, v61
	v_cvt_pk_bf16_f32 v245, v62, v63
	ds_write_b64 v191, v[244:245] offset:32768
	ds_read_b128 v[32:35], v194 offset:32768
	ds_read_b128 v[36:39], v194 offset:33792
	ds_read_b128 v[40:43], v194 offset:34816
	ds_read_b128 v[44:47], v194 offset:35840
	s_waitcnt lgkmcnt(12)
; DI int crow(int r, int hf) { return (r & 3) + 8 * (r >> 2) + 4 * hf; }
;     ...
; #pragma unroll
;       for (int i = 0; i < 2; ++i)
; #pragma unroll
;         for (int j = 0; j < 2; ++j)
; #pragma unroll
;           for (int r = 0; r < 16; ++r) {
;             const int row = m0_ + wm * 64 + i * 32 + crow(r, hf_), col = n0 + wn * 64 + j * 32 + l32_;
;             float v = acc[i][j][r];
;             if (mode == 1) { v = fmaxf(v, 0.f); v = v * v; }
;             if (V == 0 || v == 123456.789f) C[(size_t)row * ldc + col] = f2bf(v);
;           }
;     });
	global_store_dwordx4 v195, v[0:3], s[38:39] nt
	s_add_u32 s38, s38, s40
	s_addc_u32 s39, s39, 0
	global_store_dwordx4 v195, v[4:7], s[38:39] nt
	s_add_u32 s38, s38, s40
	s_addc_u32 s39, s39, 0
	global_store_dwordx4 v195, v[8:11], s[38:39] nt
	s_add_u32 s38, s38, s40
	s_addc_u32 s39, s39, 0
	global_store_dwordx4 v195, v[12:15], s[38:39] nt
	s_add_u32 s38, s38, s40
	s_addc_u32 s39, s39, 0
	v_cvt_pk_bf16_f32 v238, v64, v65
	v_cvt_pk_bf16_f32 v239, v66, v67
	ds_write_b64 v178, v[238:239] offset:32768
	v_cvt_pk_bf16_f32 v240, v68, v69
	v_cvt_pk_bf16_f32 v241, v70, v71
	ds_write_b64 v179, v[240:241] offset:32768
	v_cvt_pk_bf16_f32 v242, v72, v73
	v_cvt_pk_bf16_f32 v243, v74, v75
	ds_write_b64 v180, v[242:243] offset:32768
	v_cvt_pk_bf16_f32 v244, v76, v77
	v_cvt_pk_bf16_f32 v245, v78, v79
	ds_write_b64 v181, v[244:245] offset:32768
	v_cvt_pk_bf16_f32 v238, v80, v81
	v_cvt_pk_bf16_f32 v239, v82, v83
	ds_write_b64 v188, v[238:239] offset:32768
	v_cvt_pk_bf16_f32 v240, v84, v85
	v_cvt_pk_bf16_f32 v241, v86, v87
	ds_write_b64 v189, v[240:241] offset:32768
	v_cvt_pk_bf16_f32 v242, v88, v89
	v_cvt_pk_bf16_f32 v243, v90, v91
	ds_write_b64 v190, v[242:243] offset:32768
	v_cvt_pk_bf16_f32 v244, v92, v93
	v_cvt_pk_bf16_f32 v245, v94, v95
	ds_write_b64 v191, v[244:245] offset:32768
	ds_read_b128 v[64:67], v194 offset:32768
	ds_read_b128 v[68:71], v194 offset:33792
	ds_read_b128 v[72:75], v194 offset:34816
	ds_read_b128 v[76:79], v194 offset:35840
	s_waitcnt lgkmcnt(12)
	global_store_dwordx4 v195, v[32:35], s[38:39] nt
	s_add_u32 s38, s38, s40
	s_addc_u32 s39, s39, 0
	global_store_dwordx4 v195, v[36:39], s[38:39] nt
	s_add_u32 s38, s38, s40
	s_addc_u32 s39, s39, 0
	global_store_dwordx4 v195, v[40:43], s[38:39] nt
	s_add_u32 s38, s38, s40
	s_addc_u32 s39, s39, 0
	global_store_dwordx4 v195, v[44:47], s[38:39] nt
	s_add_u32 s38, s38, s40
	s_addc_u32 s39, s39, 0
	v_cvt_pk_bf16_f32 v238, v96, v97
	v_cvt_pk_bf16_f32 v239, v98, v99
	ds_write_b64 v178, v[238:239] offset:32768
	v_cvt_pk_bf16_f32 v240, v100, v101
	v_cvt_pk_bf16_f32 v241, v102, v103
	ds_write_b64 v179, v[240:241] offset:32768
	v_cvt_pk_bf16_f32 v242, v104, v105
	v_cvt_pk_bf16_f32 v243, v106, v107
	ds_write_b64 v180, v[242:243] offset:32768
	v_cvt_pk_bf16_f32 v244, v108, v109
	v_cvt_pk_bf16_f32 v245, v110, v111
	ds_write_b64 v181, v[244:245] offset:32768
	v_cvt_pk_bf16_f32 v238, v112, v113
	v_cvt_pk_bf16_f32 v239, v114, v115
	ds_write_b64 v188, v[238:239] offset:32768
	v_cvt_pk_bf16_f32 v240, v116, v117
	v_cvt_pk_bf16_f32 v241, v118, v119
	ds_write_b64 v189, v[240:241] offset:32768
	v_cvt_pk_bf16_f32 v242, v120, v121
	v_cvt_pk_bf16_f32 v243, v122, v123
	ds_write_b64 v190, v[242:243] offset:32768
	v_cvt_pk_bf16_f32 v244, v124, v125
	v_cvt_pk_bf16_f32 v245, v126, v127
	ds_write_b64 v191, v[244:245] offset:32768
	ds_read_b128 v[96:99], v194 offset:32768
	ds_read_b128 v[100:103], v194 offset:33792
	ds_read_b128 v[104:107], v194 offset:34816
	ds_read_b128 v[108:111], v194 offset:35840
	s_waitcnt lgkmcnt(12)
	global_store_dwordx4 v195, v[64:67], s[38:39] nt
	s_add_u32 s38, s38, s40
	s_addc_u32 s39, s39, 0
	global_store_dwordx4 v195, v[68:71], s[38:39] nt
	s_add_u32 s38, s38, s40
	s_addc_u32 s39, s39, 0
	global_store_dwordx4 v195, v[72:75], s[38:39] nt
	s_add_u32 s38, s38, s40
	s_addc_u32 s39, s39, 0
	global_store_dwordx4 v195, v[76:79], s[38:39] nt
	s_add_u32 s38, s38, s40
	s_addc_u32 s39, s39, 0
	s_waitcnt lgkmcnt(0)
	global_store_dwordx4 v195, v[96:99], s[38:39] nt
	s_add_u32 s38, s38, s40
	s_addc_u32 s39, s39, 0
	global_store_dwordx4 v195, v[100:103], s[38:39] nt
	s_add_u32 s38, s38, s40
	s_addc_u32 s39, s39, 0
	global_store_dwordx4 v195, v[104:107], s[38:39] nt
	s_add_u32 s38, s38, s40
	s_addc_u32 s39, s39, 0
	global_store_dwordx4 v195, v[108:111], s[38:39] nt
	s_branch .Lgm_epi_done
.Lgm_epi_relu:
	v_max_f32_e32 v0, 0, v0
	v_max_f32_e32 v1, 0, v1
	v_max_f32_e32 v2, 0, v2
	v_max_f32_e32 v3, 0, v3
	v_mul_f32_e32 v0, v0, v0
	v_mul_f32_e32 v1, v1, v1
	v_mul_f32_e32 v2, v2, v2
	v_mul_f32_e32 v3, v3, v3
	v_cvt_pk_bf16_f32 v238, v0, v1
	v_cvt_pk_bf16_f32 v239, v2, v3
	ds_write_b64 v178, v[238:239] offset:32768
	v_max_f32_e32 v4, 0, v4
	v_max_f32_e32 v5, 0, v5
	v_max_f32_e32 v6, 0, v6
	v_max_f32_e32 v7, 0, v7
	v_mul_f32_e32 v4, v4, v4
	v_mul_f32_e32 v5, v5, v5
	v_mul_f32_e32 v6, v6, v6
	v_mul_f32_e32 v7, v7, v7
	v_cvt_pk_bf16_f32 v240, v4, v5
	v_cvt_pk_bf16_f32 v241, v6, v7
	ds_write_b64 v179, v[240:241] offset:32768
	v_max_f32_e32 v8, 0, v8
	v_max_f32_e32 v9, 0, v9
	v_max_f32_e32 v10, 0, v10
	v_max_f32_e32 v11, 0, v11
	v_mul_f32_e32 v8, v8, v8
	v_mul_f32_e32 v9, v9, v9
	v_mul_f32_e32 v10, v10, v10
	v_mul_f32_e32 v11, v11, v11
	v_cvt_pk_bf16_f32 v242, v8, v9
	v_cvt_pk_bf16_f32 v243, v10, v11
	ds_write_b64 v180, v[242:243] offset:32768
	v_max_f32_e32 v12, 0, v12
	v_max_f32_e32 v13, 0, v13
	v_max_f32_e32 v14, 0, v14
	v_max_f32_e32 v15, 0, v15
	v_mul_f32_e32 v12, v12, v12
	v_mul_f32_e32 v13, v13, v13
	v_mul_f32_e32 v14, v14, v14
	v_mul_f32_e32 v15, v15, v15
	v_cvt_pk_bf16_f32 v244, v12, v13
	v_cvt_pk_bf16_f32 v245, v14, v15
	ds_write_b64 v181, v[244:245] offset:32768
	v_max_f32_e32 v16, 0, v16
	v_max_f32_e32 v17, 0, v17
	v_max_f32_e32 v18, 0, v18
	v_max_f32_e32 v19, 0, v19
	v_mul_f32_e32 v16, v16, v16
	v_mul_f32_e32 v17, v17, v17
	v_mul_f32_e32 v18, v18, v18
	v_mul_f32_e32 v19, v19, v19
	v_cvt_pk_bf16_f32 v238, v16, v17
	v_cvt_pk_bf16_f32 v239, v18, v19
	ds_write_b64 v188, v[238:239] offset:32768
	v_max_f32_e32 v20, 0, v20
	v_max_f32_e32 v21, 0, v21
	v_max_f32_e32 v22, 0, v22
	v_max_f32_e32 v23, 0, v23
	v_mul_f32_e32 v20, v20, v20
	v_mul_f32_e32 v21, v21, v21
	v_mul_f32_e32 v22, v22, v22
	v_mul_f32_e32 v23, v23, v23
; DI int crow(int r, int hf) { return (r & 3) + 8 * (r >> 2) + 4 * hf; }
;     ...
; #pragma unroll
;       for (int i = 0; i < 2; ++i)
; #pragma unroll
;         for (int j = 0; j < 2; ++j)
; #pragma unroll
;           for (int r = 0; r < 16; ++r) {
;             const int row = m0_ + wm * 64 + i * 32 + crow(r, hf_), col = n0 + wn * 64 + j * 32 + l32_;
;             float v = acc[i][j][r];
;             if (mode == 1) { v = fmaxf(v, 0.f); v = v * v; }
;             if (V == 0 || v == 123456.789f) C[(size_t)row * ldc + col] = f2bf(v);
;           }
;     });
	v_cvt_pk_bf16_f32 v240, v20, v21
	v_cvt_pk_bf16_f32 v241, v22, v23
	ds_write_b64 v189, v[240:241] offset:32768
	v_max_f32_e32 v24, 0, v24
	v_max_f32_e32 v25, 0, v25
	v_max_f32_e32 v26, 0, v26
	v_max_f32_e32 v27, 0, v27
	v_mul_f32_e32 v24, v24, v24
	v_mul_f32_e32 v25, v25, v25
	v_mul_f32_e32 v26, v26, v26
	v_mul_f32_e32 v27, v27, v27
	v_cvt_pk_bf16_f32 v242, v24, v25
	v_cvt_pk_bf16_f32 v243, v26, v27
	ds_write_b64 v190, v[242:243] offset:32768
	v_max_f32_e32 v28, 0, v28
	v_max_f32_e32 v29, 0, v29
	v_max_f32_e32 v30, 0, v30
	v_max_f32_e32 v31, 0, v31
	v_mul_f32_e32 v28, v28, v28
	v_mul_f32_e32 v29, v29, v29
	v_mul_f32_e32 v30, v30, v30
	v_mul_f32_e32 v31, v31, v31
	v_cvt_pk_bf16_f32 v244, v28, v29
	v_cvt_pk_bf16_f32 v245, v30, v31
	ds_write_b64 v191, v[244:245] offset:32768
	ds_read_b128 v[0:3], v194 offset:32768
	ds_read_b128 v[4:7], v194 offset:33792
	ds_read_b128 v[8:11], v194 offset:34816
	ds_read_b128 v[12:15], v194 offset:35840
	v_max_f32_e32 v32, 0, v32
	v_max_f32_e32 v33, 0, v33
	v_max_f32_e32 v34, 0, v34
	v_max_f32_e32 v35, 0, v35
	v_mul_f32_e32 v32, v32, v32
	v_mul_f32_e32 v33, v33, v33
	v_mul_f32_e32 v34, v34, v34
	v_mul_f32_e32 v35, v35, v35
	v_cvt_pk_bf16_f32 v238, v32, v33
	v_cvt_pk_bf16_f32 v239, v34, v35
	ds_write_b64 v178, v[238:239] offset:32768
	v_max_f32_e32 v36, 0, v36
	v_max_f32_e32 v37, 0, v37
	v_max_f32_e32 v38, 0, v38
	v_max_f32_e32 v39, 0, v39
	v_mul_f32_e32 v36, v36, v36
	v_mul_f32_e32 v37, v37, v37
	v_mul_f32_e32 v38, v38, v38
	v_mul_f32_e32 v39, v39, v39
	v_cvt_pk_bf16_f32 v240, v36, v37
	v_cvt_pk_bf16_f32 v241, v38, v39
	ds_write_b64 v179, v[240:241] offset:32768
	v_max_f32_e32 v40, 0, v40
	v_max_f32_e32 v41, 0, v41
	v_max_f32_e32 v42, 0, v42
	v_max_f32_e32 v43, 0, v43
	v_mul_f32_e32 v40, v40, v40
	v_mul_f32_e32 v41, v41, v41
	v_mul_f32_e32 v42, v42, v42
	v_mul_f32_e32 v43, v43, v43
	v_cvt_pk_bf16_f32 v242, v40, v41
	v_cvt_pk_bf16_f32 v243, v42, v43
	ds_write_b64 v180, v[242:243] offset:32768
	v_max_f32_e32 v44, 0, v44
	v_max_f32_e32 v45, 0, v45
	v_max_f32_e32 v46, 0, v46
	v_max_f32_e32 v47, 0, v47
	v_mul_f32_e32 v44, v44, v44
	v_mul_f32_e32 v45, v45, v45
	v_mul_f32_e32 v46, v46, v46
	v_mul_f32_e32 v47, v47, v47
	v_cvt_pk_bf16_f32 v244, v44, v45
	v_cvt_pk_bf16_f32 v245, v46, v47
	ds_write_b64 v181, v[244:245] offset:32768
	v_max_f32_e32 v48, 0, v48
	v_max_f32_e32 v49, 0, v49
	v_max_f32_e32 v50, 0, v50
	v_max_f32_e32 v51, 0, v51
	v_mul_f32_e32 v48, v48, v48
	v_mul_f32_e32 v49, v49, v49
	v_mul_f32_e32 v50, v50, v50
	v_mul_f32_e32 v51, v51, v51
	v_cvt_pk_bf16_f32 v238, v48, v49
	v_cvt_pk_bf16_f32 v239, v50, v51
	ds_write_b64 v188, v[238:239] offset:32768
	v_max_f32_e32 v52, 0, v52
	v_max_f32_e32 v53, 0, v53
	v_max_f32_e32 v54, 0, v54
	v_max_f32_e32 v55, 0, v55
	v_mul_f32_e32 v52, v52, v52
	v_mul_f32_e32 v53, v53, v53
	v_mul_f32_e32 v54, v54, v54
	v_mul_f32_e32 v55, v55, v55
	v_cvt_pk_bf16_f32 v240, v52, v53
	v_cvt_pk_bf16_f32 v241, v54, v55
	ds_write_b64 v189, v[240:241] offset:32768
	v_max_f32_e32 v56, 0, v56
	v_max_f32_e32 v57, 0, v57
	v_max_f32_e32 v58, 0, v58
	v_max_f32_e32 v59, 0, v59
	v_mul_f32_e32 v56, v56, v56
	v_mul_f32_e32 v57, v57, v57
	v_mul_f32_e32 v58, v58, v58
	v_mul_f32_e32 v59, v59, v59
	v_cvt_pk_bf16_f32 v242, v56, v57
	v_cvt_pk_bf16_f32 v243, v58, v59
	ds_write_b64 v190, v[242:243] offset:32768
	v_max_f32_e32 v60, 0, v60
	v_max_f32_e32 v61, 0, v61
	v_max_f32_e32 v62, 0, v62
	v_max_f32_e32 v63, 0, v63
	v_mul_f32_e32 v60, v60, v60
	v_mul_f32_e32 v61, v61, v61
	v_mul_f32_e32 v62, v62, v62
	v_mul_f32_e32 v63, v63, v63
	v_cvt_pk_bf16_f32 v244, v60, v61
	v_cvt_pk_bf16_f32 v245, v62, v63
	ds_write_b64 v191, v[244:245] offset:32768
	ds_read_b128 v[32:35], v194 offset:32768
	ds_read_b128 v[36:39], v194 offset:33792
	ds_read_b128 v[40:43], v194 offset:34816
	ds_read_b128 v[44:47], v194 offset:35840
	s_waitcnt lgkmcnt(12)
	global_store_dwordx4 v195, v[0:3], s[38:39] nt
	s_add_u32 s38, s38, s40
	s_addc_u32 s39, s39, 0
	global_store_dwordx4 v195, v[4:7], s[38:39] nt
	s_add_u32 s38, s38, s40
	s_addc_u32 s39, s39, 0
	global_store_dwordx4 v195, v[8:11], s[38:39] nt
	s_add_u32 s38, s38, s40
	s_addc_u32 s39, s39, 0
	global_store_dwordx4 v195, v[12:15], s[38:39] nt
	s_add_u32 s38, s38, s40
	s_addc_u32 s39, s39, 0
	v_max_f32_e32 v64, 0, v64
	v_max_f32_e32 v65, 0, v65
	v_max_f32_e32 v66, 0, v66
	v_max_f32_e32 v67, 0, v67
	v_mul_f32_e32 v64, v64, v64
	v_mul_f32_e32 v65, v65, v65
	v_mul_f32_e32 v66, v66, v66
	v_mul_f32_e32 v67, v67, v67
	v_cvt_pk_bf16_f32 v238, v64, v65
	v_cvt_pk_bf16_f32 v239, v66, v67
	ds_write_b64 v178, v[238:239] offset:32768
	v_max_f32_e32 v68, 0, v68
	v_max_f32_e32 v69, 0, v69
	v_max_f32_e32 v70, 0, v70
	v_max_f32_e32 v71, 0, v71
	v_mul_f32_e32 v68, v68, v68
	v_mul_f32_e32 v69, v69, v69
	v_mul_f32_e32 v70, v70, v70
	v_mul_f32_e32 v71, v71, v71
	v_cvt_pk_bf16_f32 v240, v68, v69
	v_cvt_pk_bf16_f32 v241, v70, v71
	ds_write_b64 v179, v[240:241] offset:32768
	v_max_f32_e32 v72, 0, v72
	v_max_f32_e32 v73, 0, v73
	v_max_f32_e32 v74, 0, v74
	v_max_f32_e32 v75, 0, v75
	v_mul_f32_e32 v72, v72, v72
	v_mul_f32_e32 v73, v73, v73
	v_mul_f32_e32 v74, v74, v74
	v_mul_f32_e32 v75, v75, v75
	v_cvt_pk_bf16_f32 v242, v72, v73
	v_cvt_pk_bf16_f32 v243, v74, v75
	ds_write_b64 v180, v[242:243] offset:32768
	v_max_f32_e32 v76, 0, v76
	v_max_f32_e32 v77, 0, v77
	v_max_f32_e32 v78, 0, v78
	v_max_f32_e32 v79, 0, v79
	v_mul_f32_e32 v76, v76, v76
	v_mul_f32_e32 v77, v77, v77
	v_mul_f32_e32 v78, v78, v78
	v_mul_f32_e32 v79, v79, v79
	v_cvt_pk_bf16_f32 v244, v76, v77
	v_cvt_pk_bf16_f32 v245, v78, v79
	ds_write_b64 v181, v[244:245] offset:32768
	v_max_f32_e32 v80, 0, v80
	v_max_f32_e32 v81, 0, v81
	v_max_f32_e32 v82, 0, v82
; DI int crow(int r, int hf) { return (r & 3) + 8 * (r >> 2) + 4 * hf; }
;     ...
; #pragma unroll
;       for (int i = 0; i < 2; ++i)
; #pragma unroll
;         for (int j = 0; j < 2; ++j)
; #pragma unroll
;           for (int r = 0; r < 16; ++r) {
;             const int row = m0_ + wm * 64 + i * 32 + crow(r, hf_), col = n0 + wn * 64 + j * 32 + l32_;
;             float v = acc[i][j][r];
;             if (mode == 1) { v = fmaxf(v, 0.f); v = v * v; }
;             if (V == 0 || v == 123456.789f) C[(size_t)row * ldc + col] = f2bf(v);
;           }
;     });
	v_max_f32_e32 v83, 0, v83
	v_mul_f32_e32 v80, v80, v80
	v_mul_f32_e32 v81, v81, v81
	v_mul_f32_e32 v82, v82, v82
	v_mul_f32_e32 v83, v83, v83
	v_cvt_pk_bf16_f32 v238, v80, v81
	v_cvt_pk_bf16_f32 v239, v82, v83
	ds_write_b64 v188, v[238:239] offset:32768
	v_max_f32_e32 v84, 0, v84
	v_max_f32_e32 v85, 0, v85
	v_max_f32_e32 v86, 0, v86
	v_max_f32_e32 v87, 0, v87
	v_mul_f32_e32 v84, v84, v84
	v_mul_f32_e32 v85, v85, v85
	v_mul_f32_e32 v86, v86, v86
	v_mul_f32_e32 v87, v87, v87
	v_cvt_pk_bf16_f32 v240, v84, v85
	v_cvt_pk_bf16_f32 v241, v86, v87
	ds_write_b64 v189, v[240:241] offset:32768
	v_max_f32_e32 v88, 0, v88
	v_max_f32_e32 v89, 0, v89
	v_max_f32_e32 v90, 0, v90
	v_max_f32_e32 v91, 0, v91
	v_mul_f32_e32 v88, v88, v88
	v_mul_f32_e32 v89, v89, v89
	v_mul_f32_e32 v90, v90, v90
	v_mul_f32_e32 v91, v91, v91
	v_cvt_pk_bf16_f32 v242, v88, v89
	v_cvt_pk_bf16_f32 v243, v90, v91
	ds_write_b64 v190, v[242:243] offset:32768
	v_max_f32_e32 v92, 0, v92
	v_max_f32_e32 v93, 0, v93
	v_max_f32_e32 v94, 0, v94
	v_max_f32_e32 v95, 0, v95
	v_mul_f32_e32 v92, v92, v92
	v_mul_f32_e32 v93, v93, v93
	v_mul_f32_e32 v94, v94, v94
	v_mul_f32_e32 v95, v95, v95
	v_cvt_pk_bf16_f32 v244, v92, v93
	v_cvt_pk_bf16_f32 v245, v94, v95
	ds_write_b64 v191, v[244:245] offset:32768
	ds_read_b128 v[64:67], v194 offset:32768
	ds_read_b128 v[68:71], v194 offset:33792
	ds_read_b128 v[72:75], v194 offset:34816
	ds_read_b128 v[76:79], v194 offset:35840
	s_waitcnt lgkmcnt(12)
	global_store_dwordx4 v195, v[32:35], s[38:39] nt
	s_add_u32 s38, s38, s40
	s_addc_u32 s39, s39, 0
	global_store_dwordx4 v195, v[36:39], s[38:39] nt
	s_add_u32 s38, s38, s40
	s_addc_u32 s39, s39, 0
	global_store_dwordx4 v195, v[40:43], s[38:39] nt
	s_add_u32 s38, s38, s40
	s_addc_u32 s39, s39, 0
	global_store_dwordx4 v195, v[44:47], s[38:39] nt
	s_add_u32 s38, s38, s40
	s_addc_u32 s39, s39, 0
	v_max_f32_e32 v96, 0, v96
	v_max_f32_e32 v97, 0, v97
	v_max_f32_e32 v98, 0, v98
	v_max_f32_e32 v99, 0, v99
	v_mul_f32_e32 v96, v96, v96
	v_mul_f32_e32 v97, v97, v97
	v_mul_f32_e32 v98, v98, v98
	v_mul_f32_e32 v99, v99, v99
	v_cvt_pk_bf16_f32 v238, v96, v97
	v_cvt_pk_bf16_f32 v239, v98, v99
	ds_write_b64 v178, v[238:239] offset:32768
	v_max_f32_e32 v100, 0, v100
	v_max_f32_e32 v101, 0, v101
	v_max_f32_e32 v102, 0, v102
	v_max_f32_e32 v103, 0, v103
	v_mul_f32_e32 v100, v100, v100
	v_mul_f32_e32 v101, v101, v101
	v_mul_f32_e32 v102, v102, v102
	v_mul_f32_e32 v103, v103, v103
	v_cvt_pk_bf16_f32 v240, v100, v101
	v_cvt_pk_bf16_f32 v241, v102, v103
	ds_write_b64 v179, v[240:241] offset:32768
	v_max_f32_e32 v104, 0, v104
	v_max_f32_e32 v105, 0, v105
	v_max_f32_e32 v106, 0, v106
	v_max_f32_e32 v107, 0, v107
	v_mul_f32_e32 v104, v104, v104
	v_mul_f32_e32 v105, v105, v105
	v_mul_f32_e32 v106, v106, v106
	v_mul_f32_e32 v107, v107, v107
	v_cvt_pk_bf16_f32 v242, v104, v105
	v_cvt_pk_bf16_f32 v243, v106, v107
	ds_write_b64 v180, v[242:243] offset:32768
	v_max_f32_e32 v108, 0, v108
	v_max_f32_e32 v109, 0, v109
	v_max_f32_e32 v110, 0, v110
	v_max_f32_e32 v111, 0, v111
	v_mul_f32_e32 v108, v108, v108
	v_mul_f32_e32 v109, v109, v109
	v_mul_f32_e32 v110, v110, v110
	v_mul_f32_e32 v111, v111, v111
	v_cvt_pk_bf16_f32 v244, v108, v109
	v_cvt_pk_bf16_f32 v245, v110, v111
	ds_write_b64 v181, v[244:245] offset:32768
	v_max_f32_e32 v112, 0, v112
	v_max_f32_e32 v113, 0, v113
	v_max_f32_e32 v114, 0, v114
	v_max_f32_e32 v115, 0, v115
	v_mul_f32_e32 v112, v112, v112
	v_mul_f32_e32 v113, v113, v113
	v_mul_f32_e32 v114, v114, v114
	v_mul_f32_e32 v115, v115, v115
	v_cvt_pk_bf16_f32 v238, v112, v113
	v_cvt_pk_bf16_f32 v239, v114, v115
	ds_write_b64 v188, v[238:239] offset:32768
	v_max_f32_e32 v116, 0, v116
	v_max_f32_e32 v117, 0, v117
	v_max_f32_e32 v118, 0, v118
	v_max_f32_e32 v119, 0, v119
	v_mul_f32_e32 v116, v116, v116
	v_mul_f32_e32 v117, v117, v117
	v_mul_f32_e32 v118, v118, v118
	v_mul_f32_e32 v119, v119, v119
	v_cvt_pk_bf16_f32 v240, v116, v117
	v_cvt_pk_bf16_f32 v241, v118, v119
	ds_write_b64 v189, v[240:241] offset:32768
	v_max_f32_e32 v120, 0, v120
	v_max_f32_e32 v121, 0, v121
	v_max_f32_e32 v122, 0, v122
	v_max_f32_e32 v123, 0, v123
	v_mul_f32_e32 v120, v120, v120
	v_mul_f32_e32 v121, v121, v121
	v_mul_f32_e32 v122, v122, v122
	v_mul_f32_e32 v123, v123, v123
	v_cvt_pk_bf16_f32 v242, v120, v121
	v_cvt_pk_bf16_f32 v243, v122, v123
	ds_write_b64 v190, v[242:243] offset:32768
	v_max_f32_e32 v124, 0, v124
	v_max_f32_e32 v125, 0, v125
	v_max_f32_e32 v126, 0, v126
	v_max_f32_e32 v127, 0, v127
	v_mul_f32_e32 v124, v124, v124
	v_mul_f32_e32 v125, v125, v125
	v_mul_f32_e32 v126, v126, v126
	v_mul_f32_e32 v127, v127, v127
	v_cvt_pk_bf16_f32 v244, v124, v125
	v_cvt_pk_bf16_f32 v245, v126, v127
	ds_write_b64 v191, v[244:245] offset:32768
	ds_read_b128 v[96:99], v194 offset:32768
	ds_read_b128 v[100:103], v194 offset:33792
	ds_read_b128 v[104:107], v194 offset:34816
	ds_read_b128 v[108:111], v194 offset:35840
	s_waitcnt lgkmcnt(12)
	global_store_dwordx4 v195, v[64:67], s[38:39] nt
	s_add_u32 s38, s38, s40
	s_addc_u32 s39, s39, 0
	global_store_dwordx4 v195, v[68:71], s[38:39] nt
	s_add_u32 s38, s38, s40
	s_addc_u32 s39, s39, 0
	global_store_dwordx4 v195, v[72:75], s[38:39] nt
	s_add_u32 s38, s38, s40
	s_addc_u32 s39, s39, 0
	global_store_dwordx4 v195, v[76:79], s[38:39] nt
	s_add_u32 s38, s38, s40
	s_addc_u32 s39, s39, 0
	s_waitcnt lgkmcnt(0)
	global_store_dwordx4 v195, v[96:99], s[38:39] nt
	s_add_u32 s38, s38, s40
	s_addc_u32 s39, s39, 0
	global_store_dwordx4 v195, v[100:103], s[38:39] nt
	s_add_u32 s38, s38, s40
	s_addc_u32 s39, s39, 0
	global_store_dwordx4 v195, v[104:107], s[38:39] nt
	s_add_u32 s38, s38, s40
	s_addc_u32 s39, s39, 0
	global_store_dwordx4 v195, v[108:111], s[38:39] nt
.Lgm_epi_done:
	s_add_u32 m0, s14, 0x18000
	s_nop 0
	global_load_lds_dwordx4 v220, s[24:25]
	s_add_u32 m0, s14, 0x18400
	s_nop 0
	global_load_lds_dwordx4 v221, s[24:25]
	s_add_u32 m0, s14, 0x18800
	s_nop 0
	global_load_lds_dwordx4 v222, s[24:25]
	s_add_u32 m0, s14, 0x18c00
	s_nop 0
	global_load_lds_dwordx4 v223, s[24:25]
	s_add_u32 s22, s22, 0x80
	s_addc_u32 s23, s23, 0
	s_add_u32 s24, s24, 0x80
	s_addc_u32 s25, s25, 0
	s_add_u32 s26, s26, 1
	s_cmp_eq_u32 s26, s50
	s_cbranch_scc0 .Lgm_cadv_done8
	s_mov_b32 s26, 0
	s_add_u32 s27, s27, s30
	s_cmp_lt_u32 s27, s29
	s_cbranch_scc1 .Lgm_cadv_new8
	s_lshl_b32 s53, s50, 7
	s_sub_u32 s22, s22, s53
	s_subb_u32 s23, s23, 0
	s_sub_u32 s24, s24, s53
	s_subb_u32 s25, s25, 0
	s_branch .Lgm_cadv_done8

; #define RAWBAR() { asm volatile("s_waitcnt vmcnt(0) lgkmcnt(0)" ::: "memory"); __builtin_amdgcn_s_barrier(); }
;     ...
;   for (int kt = 0; kt < nk; kt += 2) {
;     if (V != 1) GLDS(kt + 1, 1);
;     if (V != 2) COMPUTE(0);
;     RAWBAR();
;     if (V != 1) if (kt + 2 < nk) GLDS(kt + 2, 0);
;     if (V != 2) COMPUTE(1);
;     RAWBAR();
;   }
;     ...
;   for (int lt = blockIdx.x >> 3; lt < 16 * nN; lt += gridDim.x >> 3) {
;     int mt, nt; tile_map(lt, 16, nN, 8, 4, mt, nt);
;     const int m0 = mt * 256, n0 = nt * 256;
;     gemm_tile<V>(A + (size_t)m0 * lda, lda, K / 64, nullptr, 0, 0, Wt + (size_t)n0 * ldb, ldb, smem, [&](f32x16(&acc)[2][2], int moff) {
.Lgm_cadv_done8:
	s_add_u32 s28, s28, s30
	s_cmp_lt_u32 s28, s29
	s_cbranch_scc1 .Lgm_tile
	s_waitcnt vmcnt(0) lgkmcnt(0)
